# first XCD barrier (P0->P1 seam): the acquire-side invalidates issued behind the arrival (non-leaders) / once the cross-XCD ticket is back (leader) instead of after the release; on top of all63
# speedup vs baseline: 1.0045x; 1.0002x over previous
; __device__ __forceinline__ unsigned xb_ld(unsigned* p)              { return __hip_atomic_load(p, __ATOMIC_RELAXED, __HIP_MEMORY_SCOPE_AGENT); }
; __device__ __forceinline__ unsigned xb_add(unsigned* p, unsigned v) { return __hip_atomic_fetch_add(p, v, __ATOMIC_RELAXED, __HIP_MEMORY_SCOPE_AGENT); }
; #define XB_SPIN(cond, bar) do { unsigned _sp = 0; while (cond) { __builtin_amdgcn_s_sleep(1); \
;     if ((++_sp & 255u) == 0u) { if (xb_ld(&(bar)[XB_TMO])) break; if (_sp > XB_SPIN_CAP) { atomicAdd(&(bar)[XB_TMO], 1u); break; } } } } while (0)
; __device__ __forceinline__ void xcd_barrier(const XcdBarrier& b, const int wid) {
;     ...
;         if (nloc == 0u) { xcd_barrier_complete(bar, b.x, nloc, nx); b.st[0] = nloc; b.st[1] = nx; }
;         const unsigned old = xb_add(&bar[XB_XSUB(b.x)], 1u);
;         const unsigned gen = old / nloc;
;         if (old + 1u == (gen + 1u) * nloc) {
;             __builtin_amdgcn_fence(__ATOMIC_RELEASE, "agent");
;             asm volatile("s_waitcnt vmcnt(0)" ::: "memory");
;             const unsigned og = xb_add(&bar[XB_TOP], 1u);
;             const unsigned tg = og / nx;
;             if (og + 1u == (tg + 1u) * nx) xb_add(&bar[XB_TOPGEN], 1u);
;             else XB_SPIN(xb_ld(&bar[XB_TOPGEN]) == tg, bar);
;             __builtin_amdgcn_fence(__ATOMIC_ACQUIRE, "agent");
;             xb_add(&bar[XB_XGEN(b.x)], 1u);
;             asm volatile("s_waitcnt vmcnt(0)" ::: "memory");
;         } else {
;             XB_SPIN(xb_ld(&bar[XB_XGEN(b.x)]) == gen, bar);
.LBB0_225:
	v_readlane_b32 s2, v254, 8
	s_lshl_b32 s2, s2, 8
	v_readlane_b32 s4, v254, 6
	v_readlane_b32 s5, v254, 7
	s_add_u32 s2, s4, s2
	s_addc_u32 s3, s5, 0
	v_mov_b32_e32 v1, 0x1000
	v_mov_b32_e32 v3, 1
	global_atomic_add v3, v1, v3, s[2:3] offset:1024 sc0
	v_cvt_f32_u32_e32 v1, v2
	v_sub_u32_e32 v4, 0, v2
	v_rcp_iflag_f32_e32 v1, v1
	s_nop 0
	v_mul_f32_e32 v1, 0x4f7ffffe, v1
	v_cvt_u32_f32_e32 v1, v1
	v_mul_lo_u32 v4, v4, v1
	v_mul_hi_u32 v4, v1, v4
	v_add_u32_e32 v1, v1, v4
	s_waitcnt vmcnt(0)
	v_mul_hi_u32 v1, v3, v1
	v_mul_lo_u32 v4, v1, v2
	v_sub_u32_e32 v4, v3, v4
	v_add_u32_e32 v5, 1, v1
	v_cmp_ge_u32_e32 vcc, v4, v2
	v_add_u32_e32 v3, 1, v3
	s_nop 0
	v_cndmask_b32_e32 v1, v1, v5, vcc
	v_sub_u32_e32 v5, v4, v2
	v_cndmask_b32_e32 v4, v4, v5, vcc
	v_add_u32_e32 v5, 1, v1
	v_cmp_ge_u32_e32 vcc, v4, v2
	s_nop 1
	v_cndmask_b32_e32 v1, v1, v5, vcc
	v_mul_lo_u32 v4, v2, v1
	v_add_u32_e32 v2, v4, v2
	v_cmp_ne_u32_e32 vcc, v3, v2
	s_and_saveexec_b64 s[4:5], vcc
	s_xor_b64 s[4:5], exec, s[4:5]
	s_cbranch_execz .LBB0_239
	s_waitcnt lgkmcnt(0)
	buffer_inv sc1
	v_mov_b32_e32 v0, 0
	s_add_u32 s10, s86, 0x7500
	s_addc_u32 s11, s87, 0
	global_load_dword v0, v0, s[10:11] sc1
	s_waitcnt vmcnt(0)
	v_cmp_eq_u32_e32 vcc, v0, v1
	s_and_saveexec_b64 s[6:7], vcc
	s_cbranch_execz .LBB0_238
	s_add_u32 s8, s86, 0x4200
	s_addc_u32 s9, s87, 0
	s_mov_b32 s22, 1
	s_mov_b64 s[12:13], 0
	v_mov_b32_e32 v0, 0
	s_branch .LBB0_229

; __device__ __forceinline__ unsigned xb_ld(unsigned* p)              { return __hip_atomic_load(p, __ATOMIC_RELAXED, __HIP_MEMORY_SCOPE_AGENT); }
; #define XB_SPIN(cond, bar) do { unsigned _sp = 0; while (cond) { __builtin_amdgcn_s_sleep(1); \
;     if ((++_sp & 255u) == 0u) { if (xb_ld(&(bar)[XB_TMO])) break; if (_sp > XB_SPIN_CAP) { atomicAdd(&(bar)[XB_TMO], 1u); break; } } } } while (0)
; __device__ __forceinline__ void xcd_barrier(const XcdBarrier& b, const int wid) {
;     ...
;             XB_SPIN(xb_ld(&bar[XB_XGEN(b.x)]) == gen, bar);
;             __builtin_amdgcn_fence(__ATOMIC_ACQUIRE, "agent");
;             asm volatile("s_waitcnt vmcnt(0)" ::: "memory");
.LBB0_238:
	s_or_b64 exec, exec, s[6:7]
	s_waitcnt vmcnt(0)
	s_waitcnt vmcnt(0)

; __device__ __forceinline__ unsigned xb_ld(unsigned* p)              { return __hip_atomic_load(p, __ATOMIC_RELAXED, __HIP_MEMORY_SCOPE_AGENT); }
; __device__ __forceinline__ unsigned xb_add(unsigned* p, unsigned v) { return __hip_atomic_fetch_add(p, v, __ATOMIC_RELAXED, __HIP_MEMORY_SCOPE_AGENT); }
; #define XB_SPIN(cond, bar) do { unsigned _sp = 0; while (cond) { __builtin_amdgcn_s_sleep(1); \
;     if ((++_sp & 255u) == 0u) { if (xb_ld(&(bar)[XB_TMO])) break; if (_sp > XB_SPIN_CAP) { atomicAdd(&(bar)[XB_TMO], 1u); break; } } } } while (0)
; __device__ __forceinline__ void xcd_barrier(const XcdBarrier& b, const int wid) {
;     ...
;             const unsigned og = xb_add(&bar[XB_TOP], 1u);
;             const unsigned tg = og / nx;
;             if (og + 1u == (tg + 1u) * nx) xb_add(&bar[XB_TOPGEN], 1u);
;             else XB_SPIN(xb_ld(&bar[XB_TOPGEN]) == tg, bar);
.LBB0_242:
	s_or_b64 exec, exec, s[6:7]
	v_cvt_f32_u32_e32 v3, v0
	s_waitcnt vmcnt(0)
	buffer_inv sc1
	v_readfirstlane_b32 s4, v2
	s_add_u32 s6, s86, 0x7500
	s_addc_u32 s7, s87, 0
	v_rcp_iflag_f32_e32 v3, v3
	v_add_u32_e32 v1, s4, v1
	v_add_u32_e32 v4, 1, v1
	s_mov_b64 s[8:9], -1
	v_mul_f32_e32 v2, 0x4f7ffffe, v3
	v_cvt_u32_f32_e32 v2, v2
	v_sub_u32_e32 v3, 0, v0
	v_mul_lo_u32 v3, v3, v2
	v_mul_hi_u32 v3, v2, v3
	v_add_u32_e32 v2, v2, v3
	v_mul_hi_u32 v2, v1, v2
	v_mul_lo_u32 v3, v2, v0
	v_sub_u32_e32 v1, v1, v3
	v_add_u32_e32 v5, 1, v2
	v_cmp_ge_u32_e32 vcc, v1, v0
	v_sub_u32_e32 v3, v1, v0
	s_nop 0
	v_cndmask_b32_e32 v2, v2, v5, vcc
	v_cndmask_b32_e32 v1, v1, v3, vcc
	v_add_u32_e32 v3, 1, v2
	v_cmp_ge_u32_e32 vcc, v1, v0
	s_nop 1
	v_cndmask_b32_e32 v2, v2, v3, vcc
	v_mul_lo_u32 v1, v0, v2
	v_add_u32_e32 v0, v1, v0
	v_cmp_ne_u32_e32 vcc, v4, v0
	v_mov_b64_e32 v[0:1], s[6:7]
	s_and_saveexec_b64 s[4:5], vcc
	s_cbranch_execz .LBB0_254
	v_mov_b32_e32 v0, 0
	global_load_dword v1, v0, s[6:7] sc1
	s_mov_b64 s[12:13], 0
	s_waitcnt vmcnt(0)
	v_cmp_eq_u32_e32 vcc, v1, v2
	s_and_saveexec_b64 s[10:11], vcc
	s_cbranch_execz .LBB0_253
	s_add_u32 s8, s86, 0x4200
	s_addc_u32 s9, s87, 0
	s_mov_b32 s22, 1
	s_branch .LBB0_246

; __device__ __forceinline__ unsigned xb_add(unsigned* p, unsigned v) { return __hip_atomic_fetch_add(p, v, __ATOMIC_RELAXED, __HIP_MEMORY_SCOPE_AGENT); }
; __device__ __forceinline__ void xcd_barrier(const XcdBarrier& b, const int wid) {
;     ...
;             __builtin_amdgcn_fence(__ATOMIC_ACQUIRE, "agent");
;             xb_add(&bar[XB_XGEN(b.x)], 1u);
;             asm volatile("s_waitcnt vmcnt(0)" ::: "memory");
.LBB0_256:
	s_or_b64 exec, exec, s[4:5]
	v_mov_b32_e32 v0, 0x2000
	v_mov_b32_e32 v1, 1
	s_waitcnt vmcnt(0)
	global_atomic_add v0, v1, s[2:3] offset:1024
	s_waitcnt vmcnt(0)
